# mix->cross and cross->mem_o grid barriers replaced by a 4-workgroup flag sync through L2 among the workgroups that own the same row tile (cross items remapped to the GEMM tile walk; falls back to the
# speedup vs baseline: 1.0053x; 1.0053x over previous
_Z14fwd_megakernel6Params:
	s_load_dwordx4 s[92:95], s[0:1], 0x140
	s_load_dword s64, s[0:1], 0x150
	s_add_u32 s4, s0, 0x148
	s_addc_u32 s5, s1, 0
	s_getreg_b32 s3, hwreg(HW_REG_XCC_ID, 0, 4)
	s_waitcnt lgkmcnt(0)
	s_add_u32 s14, s92, 0xb500900
	v_and_b32_e32 v166, 0x3ff, v0
	s_addc_u32 s15, s93, 0
	s_and_b32 s3, s3, 15
	v_cmp_eq_u32_e64 s[74:75], 0, v166
	s_and_saveexec_b64 s[6:7], s[74:75]
	s_cbranch_execz .LBB0_3
	s_mov_b64 s[8:9], exec
	v_mbcnt_lo_u32_b32 v1, s8, 0
	v_mbcnt_hi_u32_b32 v1, s9, v1
	v_cmp_eq_u32_e32 vcc, 0, v1
	s_and_b64 s[10:11], exec, vcc
	s_mov_b64 exec, s[10:11]
	s_cbranch_execz .LBB0_3
	s_lshl_b32 s10, s3, 8
	s_bcnt1_i32_b64 s8, s[8:9]
	v_mov_b32_e32 v1, s10
	v_mov_b32_e32 v2, s8
	global_atomic_add v2, v1, v2, s[14:15] offset:1024 sc0
	s_waitcnt vmcnt(0)
	v_readfirstlane_b32 s8, v2
	s_nop 1
	v_writelane_b32 v240, s8, 62
	s_and_b32 s10, s2, 7
	s_lshl_b32 s10, s10, 2
	s_add_u32 s10, s10, 0x1800
	s_lshl_b32 s11, 1, s3
	v_mov_b32_e32 v1, s10
	v_mov_b32_e32 v2, s11
	global_atomic_or v1, v2, s[14:15]
.LBB0_3:
	s_or_b64 exec, exec, s[6:7]
	v_writelane_b32 v240, s3, 61
	v_writelane_b32 v240, 0, 63
	v_writelane_b32 v240, 0, 60
	v_writelane_b32 v240, 0, 59
	v_writelane_b32 v240, 0, 58
	v_writelane_b32 v240, 0, 57
	v_writelane_b32 v240, 0, 56
	s_load_dwordx16 s[16:31], s[0:1], 0x0
	v_mov_b32_e32 v2, v166
	s_cmp_lg_u32 s2, 0
	s_waitcnt lgkmcnt(0)
	v_writelane_b32 v245, s16, 0
	s_nop 1
	v_writelane_b32 v245, s17, 1
	v_writelane_b32 v245, s18, 2
	v_writelane_b32 v245, s19, 3
	v_writelane_b32 v245, s20, 4
	v_writelane_b32 v245, s21, 5
	v_writelane_b32 v245, s22, 6
	v_writelane_b32 v245, s23, 7
	v_writelane_b32 v245, s24, 8
	v_writelane_b32 v245, s25, 9
	v_writelane_b32 v245, s26, 10
	v_writelane_b32 v245, s27, 11
	v_writelane_b32 v245, s28, 12
	v_writelane_b32 v245, s29, 13
	v_writelane_b32 v245, s30, 14
	v_writelane_b32 v245, s31, 15
	s_cbranch_scc1 .LBB0_9
	v_ashrrev_i32_e32 v3, 31, v2
	v_lshl_add_u64 v[4:5], v[2:3], 2, s[92:93]
	v_add_co_u32_e32 v8, vcc, 0xb500000, v4
	v_mov_b32_e32 v6, 0
	s_nop 0
	v_addc_co_u32_e32 v9, vcc, 0, v5, vcc
	v_cmp_gt_i32_e32 vcc, 2, v2
	global_store_dword v[8:9], v6, off offset:256
	s_and_saveexec_b64 s[6:7], vcc
	s_cbranch_execz .LBB0_8
	s_load_dwordx16 s[16:31], s[0:1], 0x0
	v_lshlrev_b32_e32 v10, 8, v2
	v_ashrrev_i32_e32 v11, 31, v10
	s_mov_b64 s[8:9], 0
	v_mov_b32_e32 v7, v6
	s_waitcnt lgkmcnt(0)
	v_mov_b32_e32 v8, s26
	v_mov_b32_e32 v9, s27
	v_lshl_add_u64 v[8:9], v[10:11], 2, v[8:9]

.LBB0_1298:
	s_waitcnt vmcnt(0)
	s_waitcnt lgkmcnt(0)
	s_barrier
	s_and_saveexec_b64 s[0:1], s[74:75]
	s_movk_i32 s46, 0x3fff
	s_cbranch_execz .LBB0_1351
	v_readlane_b32 s28, v240, 56
	s_add_u32 s24, s92, 0xb500900
	s_addc_u32 s25, s93, 0
	s_nop 1
	s_cmp_lg_u32 s28, 0
	s_cbranch_scc1 .Lss1_have
	s_mov_b64 exec, 0xff
	v_mbcnt_lo_u32_b32 v0, -1, 0
	v_lshlrev_b32_e32 v0, 2, v0
	v_add_u32_e32 v0, 0x1800, v0
	global_load_dword v1, v0, s[24:25] sc0 sc1
	s_waitcnt vmcnt(0)
	v_bcnt_u32_b32 v1, v1, 0
	v_cmp_ne_u32_e32 vcc, 1, v1
	s_nop 3
	s_cmp_eq_u64 vcc, 0
	s_cselect_b32 s28, 1, 2
	s_cmp_eq_u32 s94, 0x100
	s_cselect_b32 s28, s28, 2
	s_mov_b64 exec, 1
	s_nop 0
	v_writelane_b32 v240, s28, 56
.Lss1_have:
	s_cmp_eq_u32 s28, 1
	s_cbranch_scc0 .Lss1_normal
	s_waitcnt vmcnt(0) lgkmcnt(0)
	v_readlane_b32 s26, v240, 57
	v_readlane_b32 s27, v241, 19
	s_nop 3
	s_add_i32 s26, s26, 1
	s_nop 1
	v_writelane_b32 v240, s26, 57
	v_mov_b32_e32 v0, s27
	v_lshlrev_b32_e32 v0, 2, v0
	v_add_u32_e32 v0, 0x1c00, v0
	v_mov_b32_e32 v1, s26
	global_store_dword v0, v1, s[24:25]
	s_mov_b64 exec, 15
	v_mbcnt_lo_u32_b32 v2, -1, 0
	s_and_b32 s27, s27, 0xffffff9f
	v_lshl_add_u32 v2, v2, 5, s27
	v_lshlrev_b32_e32 v2, 2, v2
	v_add_u32_e32 v2, 0x1c00, v2
.Lss1_p:
	global_load_dword v3, v2, s[24:25] sc1
	s_waitcnt vmcnt(0)
	v_cmp_gt_u32_e32 vcc, s26, v3
	s_cbranch_vccz .Lss1_ok
	s_sleep 1
	s_branch .Lss1_p
.Lss1_ok:
	s_mov_b64 exec, 1
	buffer_inv sc1
	s_waitcnt vmcnt(0)
	s_branch .LBB0_1351

.Lnc11_okf:
.Lnc11_done:
.LBB0_1407:
	s_or_b64 exec, exec, s[0:1]
	v_readlane_b32 s0, v244, 20
	v_readlane_b32 s1, v244, 21
	s_andn2_b64 vcc, exec, s[0:1]
	s_barrier
	s_cbranch_vccnz .LBB0_1439
	v_readlane_b32 s0, v240, 27
	s_lshl_b32 s44, s0, 2
	s_mov_b32 s45, s2
	s_cmp_eq_u32 s94, 0x100
	s_cbranch_scc0 .Lcr_keep
	s_lshr_b32 s64, s2, 3
	s_and_b32 s45, s2, 7
	s_lshl_b32 s45, s45, 3
	s_lshr_b32 s1, s64, 4
	s_lshl_b32 s1, s1, 2
	s_add_u32 s45, s45, s1
	s_and_b32 s1, s64, 3
	s_add_u32 s45, s45, s1
	s_bfe_u32 s1, s64, 0x20002
	s_lshl_b32 s1, s1, 4
	s_and_b32 s64, s45, 15
	s_or_b32 s1, s1, s64
	s_lshr_b32 s45, s45, 4
	s_lshl_b32 s45, s45, 6
	s_or_b32 s45, s45, s1
.Lcr_keep:
	s_mov_b32 s64, s45
	v_readlane_b32 s1, v240, 28
	s_branch .LBB0_1410

.LBB0_1439:
	s_waitcnt vmcnt(0)
	s_barrier
	s_and_saveexec_b64 s[0:1], s[74:75]
	s_cbranch_execz .LBB0_1492
	v_readlane_b32 s28, v240, 56
	s_add_u32 s24, s92, 0xb500900
	s_addc_u32 s25, s93, 0
	s_nop 1
	s_cmp_lg_u32 s28, 0
	s_cbranch_scc1 .Lss2_have
	s_mov_b64 exec, 0xff
	v_mbcnt_lo_u32_b32 v0, -1, 0
	v_lshlrev_b32_e32 v0, 2, v0
	v_add_u32_e32 v0, 0x1800, v0
	global_load_dword v1, v0, s[24:25] sc0 sc1
	s_waitcnt vmcnt(0)
	v_bcnt_u32_b32 v1, v1, 0
	v_cmp_ne_u32_e32 vcc, 1, v1
	s_nop 3
	s_cmp_eq_u64 vcc, 0
	s_cselect_b32 s28, 1, 2
	s_cmp_eq_u32 s94, 0x100
	s_cselect_b32 s28, s28, 2
	s_mov_b64 exec, 1
	s_nop 0
	v_writelane_b32 v240, s28, 56
